# merge2 f32 epilogue de-serialised like ffn2 (invariants once per tile, 16 row loads per half before LDS staging, unrolled chunks, counted waits)
# speedup vs baseline: 1.0183x; 1.0072x over previous
.LBB0_271:
	s_add_i32 s14, s26, 0xffffe000
	s_lshr_b32 s14, s14, 11
	s_add_i32 s15, s14, 1
	s_cmpk_gt_u32 s26, 0x1fff
	s_cselect_b32 s15, s15, 0
	s_mul_i32 s16, s82, 9
	s_add_i32 s15, s15, s16
	s_mul_hi_u32 s16, s15, 0x6000
	s_mulk_i32 s15, 0x6000
	s_add_u32 s15, s12, s15
	s_addc_u32 s45, s13, s16
	s_load_dwordx4 s[84:87], s[10:11], 0x108
	s_load_dwordx2 s[16:17], s[10:11], 0x118
	s_lshl_b64 s[40:41], s[30:31], 2
	s_add_u32 s44, s15, s40
	s_addc_u32 s45, s45, s41
	s_lshl_b64 s[30:31], s[36:37], 2
	s_waitcnt lgkmcnt(0)
	s_add_u32 s15, s16, s30
	s_addc_u32 s17, s17, s31
	s_add_u32 s16, s15, s40
	s_addc_u32 s17, s17, s41
	s_add_u32 s8, s8, s40
	s_addc_u32 s9, s9, s41
	s_lshl_b64 s[30:31], s[26:27], 3
	s_add_u32 s30, s56, s30
	v_mov_b32_e32 v89, v254
	s_addc_u32 s31, s83, s31
	s_add_u32 s36, s84, s40
	v_lshlrev_b32_e32 v64, 4, v89
	v_and_b32_e32 v148, 0x1f0, v64
	v_lshrrev_b32_e32 v64, 2, v89
	s_addc_u32 s37, s85, s41
	v_and_b32_e32 v64, 12, v64
	s_add_u32 s40, s86, s40
	v_and_b32_e32 v65, 0x4f, v89
	v_mul_u32_u24_e32 v64, 0x210, v64
	s_addc_u32 s41, s87, s41
	v_lshl_add_u32 v91, v65, 2, v64
	v_lshl_add_u64 v[64:65], s[44:45], 0, v[148:149]
	s_mov_b32 s14, 0
	v_ashrrev_i32_e32 v90, 7, v89
	v_lshl_add_u64 v[76:77], s[8:9], 0, v[148:149]
	v_lshl_add_u64 v[78:79], v[64:65], 0, s[72:73]
	v_lshl_add_u64 v[80:81], s[16:17], 0, v[148:149]
	v_lshl_add_u64 v[82:83], s[36:37], 0, v[148:149]
	v_lshl_add_u64 v[84:85], s[40:41], 0, v[148:149]
	s_waitcnt vmcnt(0)
	global_load_dwordx4 v[160:163], v[78:79], off
	global_load_dwordx4 v[164:167], v[82:83], off
	global_load_dwordx4 v[168:171], v[84:85], off
	s_mov_b64 s[8:9], -1
	s_branch .LBB0_273

.LBB0_273:
	v_cmp_eq_u32_e32 vcc, s14, v90
	s_lshl_b32 s15, s14, 6
	v_lshrrev_b32_e32 v92, 5, v89
	v_add_u32_e32 v94, s15, v92
	v_mov_b32_e32 v95, 0
	v_mad_u32_u24 v93, v92, s48, v148
	v_lshlrev_b64 v[96:97], 12, v[94:95]
	v_lshlrev_b32_e32 v94, 1, v94
	v_lshl_add_u64 v[98:99], v[80:81], 0, v[96:97]
	v_lshl_add_u64 v[100:101], v[76:77], 0, v[96:97]
	v_lshl_add_u64 v[102:103], v[94:95], 2, s[30:31]
	s_mov_b64 s[16:17], 0x8000
	global_load_dwordx2 v[172:173], v[102:103], off
	global_load_dwordx4 v[188:191], v[100:101], off
	v_lshl_add_u64 v[100:101], v[100:101], 0, s[16:17]
	global_load_dwordx2 v[174:175], v[102:103], off offset:64
	global_load_dwordx4 v[192:195], v[100:101], off
	v_lshl_add_u64 v[100:101], v[100:101], 0, s[16:17]
	global_load_dwordx2 v[176:177], v[102:103], off offset:128
	global_load_dwordx4 v[196:199], v[100:101], off
	v_lshl_add_u64 v[100:101], v[100:101], 0, s[16:17]
	global_load_dwordx2 v[178:179], v[102:103], off offset:192
	global_load_dwordx4 v[200:203], v[100:101], off
	v_lshl_add_u64 v[100:101], v[100:101], 0, s[16:17]
	global_load_dwordx2 v[180:181], v[102:103], off offset:256
	global_load_dwordx4 v[204:207], v[100:101], off
	v_lshl_add_u64 v[100:101], v[100:101], 0, s[16:17]
	global_load_dwordx2 v[182:183], v[102:103], off offset:320
	global_load_dwordx4 v[208:211], v[100:101], off
	v_lshl_add_u64 v[100:101], v[100:101], 0, s[16:17]
	global_load_dwordx2 v[184:185], v[102:103], off offset:384
	global_load_dwordx4 v[212:215], v[100:101], off
	v_lshl_add_u64 v[100:101], v[100:101], 0, s[16:17]
	global_load_dwordx2 v[186:187], v[102:103], off offset:448
	global_load_dwordx4 v[216:219], v[100:101], off
	s_barrier
	s_and_saveexec_b64 s[36:37], vcc
	s_cbranch_execz .LBB0_275
	v_add_u32_e32 v64, 0x8000, v91
	v_add_u32_e32 v65, 0x8400, v91
	ds_write2_b32 v64, v44, v40 offset1:16
	ds_write2_b32 v64, v45, v41 offset0:132 offset1:148
	ds_write2_b32 v65, v46, v42 offset0:8 offset1:24
	ds_write2_b32 v65, v47, v43 offset0:140 offset1:156
	ds_write2_b32 v64, v36, v32 offset0:32 offset1:48
	ds_write2_b32 v64, v37, v33 offset0:164 offset1:180
	ds_write2_b32 v65, v38, v34 offset0:40 offset1:56
	ds_write2_b32 v65, v39, v35 offset0:172 offset1:188
	v_add_u32_e32 v64, 0xa000, v91
	v_add_u32_e32 v65, 0xa400, v91
	ds_write2_b32 v64, v28, v24 offset0:64 offset1:80
	ds_write2_b32 v64, v29, v25 offset0:196 offset1:212
	ds_write2_b32 v65, v30, v26 offset0:72 offset1:88
	ds_write2_b32 v65, v31, v27 offset0:204 offset1:220
	ds_write2_b32 v64, v20, v16 offset0:96 offset1:112
	ds_write2_b32 v64, v21, v17 offset0:228 offset1:244
	ds_write2_b32 v65, v22, v18 offset0:104 offset1:120
	ds_write2_b32 v65, v23, v19 offset0:236 offset1:252
	v_add_u32_e32 v64, 0xc000, v91
	v_add_u32_e32 v65, 0xc400, v91
	v_add_u32_e32 v66, 0xc800, v91
	ds_write2_b32 v64, v12, v8 offset0:128 offset1:144
	ds_write2_b32 v65, v13, v9 offset0:4 offset1:20
	ds_write2_b32 v65, v14, v10 offset0:136 offset1:152
	ds_write2_b32 v66, v15, v11 offset0:12 offset1:28
	ds_write2_b32 v64, v4, v0 offset0:160 offset1:176
	ds_write2_b32 v65, v5, v1 offset0:36 offset1:52
	ds_write2_b32 v65, v6, v2 offset0:168 offset1:184
	ds_write2_b32 v66, v7, v3 offset0:44 offset1:60
	v_add_u32_e32 v64, 0xe000, v91
	v_add_u32_e32 v65, 0xe400, v91
	v_add_u32_e32 v66, 0xe800, v91
	ds_write2_b32 v64, v48, v52 offset0:192 offset1:208
	ds_write2_b32 v65, v49, v53 offset0:68 offset1:84
	ds_write2_b32 v65, v50, v54 offset0:200 offset1:216
	ds_write2_b32 v66, v51, v55 offset0:76 offset1:92
	ds_write2_b32 v64, v56, v60 offset0:224 offset1:240
	ds_write2_b32 v65, v57, v61 offset0:100 offset1:116
	ds_write2_b32 v65, v58, v62 offset0:232 offset1:248
	ds_write2_b32 v66, v59, v63 offset0:108 offset1:124
.LBB0_275:
	s_or_b64 exec, exec, s[36:37]
	s_xor_b64 s[36:37], s[8:9], -1
	s_lshl_b32 s14, s14, 6
	s_mov_b32 s15, 0
	s_waitcnt lgkmcnt(0)
	s_barrier
	ds_read_b128 v[220:223], v93 offset:32768
	ds_read_b128 v[224:227], v93 offset:36992
	ds_read_b128 v[228:231], v93 offset:41216
	ds_read_b128 v[232:235], v93 offset:45440
	ds_read_b128 v[236:239], v93 offset:49664
	ds_read_b128 v[240:243], v93 offset:53888
	ds_read_b128 v[244:247], v93 offset:58112
	ds_read_b128 v[248:251], v93 offset:62336
	s_andn2_b64 vcc, exec, s[28:29]
	s_cbranch_vccnz .Lm2epi_plain
	s_waitcnt vmcnt(14)
	v_pk_add_f32 v[188:189], v[188:189], v[172:173] op_sel_hi:[1,0] neg_lo:[0,1] neg_hi:[0,1]
	v_pk_add_f32 v[190:191], v[190:191], v[172:173] op_sel_hi:[1,0] neg_lo:[0,1] neg_hi:[0,1]
	v_pk_mul_f32 v[188:189], v[188:189], v[172:173] op_sel:[0,1]
	v_pk_mul_f32 v[190:191], v[190:191], v[172:173] op_sel:[0,1]
	v_pk_fma_f32 v[188:189], v[188:189], v[164:165], v[168:169]
	v_pk_fma_f32 v[190:191], v[190:191], v[166:167], v[170:171]
	v_pk_mul_f32 v[188:189], v[188:189], s[54:55] op_sel_hi:[1,0]
	v_pk_mul_f32 v[190:191], v[190:191], s[54:55] op_sel_hi:[1,0]
	s_waitcnt lgkmcnt(7)
	v_pk_fma_f32 v[220:221], v[220:221], v[160:161], v[188:189]
	v_pk_fma_f32 v[222:223], v[222:223], v[162:163], v[190:191]
	global_store_dwordx4 v[98:99], v[220:223], off sc1
	v_lshl_add_u64 v[98:99], v[98:99], 0, s[16:17]
	s_waitcnt vmcnt(13)
	v_pk_add_f32 v[192:193], v[192:193], v[174:175] op_sel_hi:[1,0] neg_lo:[0,1] neg_hi:[0,1]
	v_pk_add_f32 v[194:195], v[194:195], v[174:175] op_sel_hi:[1,0] neg_lo:[0,1] neg_hi:[0,1]
	v_pk_mul_f32 v[192:193], v[192:193], v[174:175] op_sel:[0,1]
	v_pk_mul_f32 v[194:195], v[194:195], v[174:175] op_sel:[0,1]
	v_pk_fma_f32 v[192:193], v[192:193], v[164:165], v[168:169]
	v_pk_fma_f32 v[194:195], v[194:195], v[166:167], v[170:171]
	v_pk_mul_f32 v[192:193], v[192:193], s[54:55] op_sel_hi:[1,0]
	v_pk_mul_f32 v[194:195], v[194:195], s[54:55] op_sel_hi:[1,0]
	s_waitcnt lgkmcnt(6)
	v_pk_fma_f32 v[224:225], v[224:225], v[160:161], v[192:193]
	v_pk_fma_f32 v[226:227], v[226:227], v[162:163], v[194:195]
	global_store_dwordx4 v[98:99], v[224:227], off sc1
	v_lshl_add_u64 v[98:99], v[98:99], 0, s[16:17]
	s_waitcnt vmcnt(12)
	v_pk_add_f32 v[196:197], v[196:197], v[176:177] op_sel_hi:[1,0] neg_lo:[0,1] neg_hi:[0,1]
	v_pk_add_f32 v[198:199], v[198:199], v[176:177] op_sel_hi:[1,0] neg_lo:[0,1] neg_hi:[0,1]
	v_pk_mul_f32 v[196:197], v[196:197], v[176:177] op_sel:[0,1]
	v_pk_mul_f32 v[198:199], v[198:199], v[176:177] op_sel:[0,1]
	v_pk_fma_f32 v[196:197], v[196:197], v[164:165], v[168:169]
	v_pk_fma_f32 v[198:199], v[198:199], v[166:167], v[170:171]
	v_pk_mul_f32 v[196:197], v[196:197], s[54:55] op_sel_hi:[1,0]
	v_pk_mul_f32 v[198:199], v[198:199], s[54:55] op_sel_hi:[1,0]
	s_waitcnt lgkmcnt(5)
	v_pk_fma_f32 v[228:229], v[228:229], v[160:161], v[196:197]
	v_pk_fma_f32 v[230:231], v[230:231], v[162:163], v[198:199]
	global_store_dwordx4 v[98:99], v[228:231], off sc1
	v_lshl_add_u64 v[98:99], v[98:99], 0, s[16:17]
	s_waitcnt vmcnt(11)
	v_pk_add_f32 v[200:201], v[200:201], v[178:179] op_sel_hi:[1,0] neg_lo:[0,1] neg_hi:[0,1]
	v_pk_add_f32 v[202:203], v[202:203], v[178:179] op_sel_hi:[1,0] neg_lo:[0,1] neg_hi:[0,1]
	v_pk_mul_f32 v[200:201], v[200:201], v[178:179] op_sel:[0,1]
	v_pk_mul_f32 v[202:203], v[202:203], v[178:179] op_sel:[0,1]
	v_pk_fma_f32 v[200:201], v[200:201], v[164:165], v[168:169]
	v_pk_fma_f32 v[202:203], v[202:203], v[166:167], v[170:171]
	v_pk_mul_f32 v[200:201], v[200:201], s[54:55] op_sel_hi:[1,0]
	v_pk_mul_f32 v[202:203], v[202:203], s[54:55] op_sel_hi:[1,0]
	s_waitcnt lgkmcnt(4)
	v_pk_fma_f32 v[232:233], v[232:233], v[160:161], v[200:201]
	v_pk_fma_f32 v[234:235], v[234:235], v[162:163], v[202:203]
	global_store_dwordx4 v[98:99], v[232:235], off sc1
	v_lshl_add_u64 v[98:99], v[98:99], 0, s[16:17]
	s_waitcnt vmcnt(10)
	v_pk_add_f32 v[204:205], v[204:205], v[180:181] op_sel_hi:[1,0] neg_lo:[0,1] neg_hi:[0,1]
	v_pk_add_f32 v[206:207], v[206:207], v[180:181] op_sel_hi:[1,0] neg_lo:[0,1] neg_hi:[0,1]
	v_pk_mul_f32 v[204:205], v[204:205], v[180:181] op_sel:[0,1]
	v_pk_mul_f32 v[206:207], v[206:207], v[180:181] op_sel:[0,1]
	v_pk_fma_f32 v[204:205], v[204:205], v[164:165], v[168:169]
	v_pk_fma_f32 v[206:207], v[206:207], v[166:167], v[170:171]
	v_pk_mul_f32 v[204:205], v[204:205], s[54:55] op_sel_hi:[1,0]
	v_pk_mul_f32 v[206:207], v[206:207], s[54:55] op_sel_hi:[1,0]
	s_waitcnt lgkmcnt(3)
	v_pk_fma_f32 v[236:237], v[236:237], v[160:161], v[204:205]
	v_pk_fma_f32 v[238:239], v[238:239], v[162:163], v[206:207]
	global_store_dwordx4 v[98:99], v[236:239], off sc1
	v_lshl_add_u64 v[98:99], v[98:99], 0, s[16:17]
	s_waitcnt vmcnt(9)
	v_pk_add_f32 v[208:209], v[208:209], v[182:183] op_sel_hi:[1,0] neg_lo:[0,1] neg_hi:[0,1]
	v_pk_add_f32 v[210:211], v[210:211], v[182:183] op_sel_hi:[1,0] neg_lo:[0,1] neg_hi:[0,1]
	v_pk_mul_f32 v[208:209], v[208:209], v[182:183] op_sel:[0,1]
	v_pk_mul_f32 v[210:211], v[210:211], v[182:183] op_sel:[0,1]
	v_pk_fma_f32 v[208:209], v[208:209], v[164:165], v[168:169]
	v_pk_fma_f32 v[210:211], v[210:211], v[166:167], v[170:171]
	v_pk_mul_f32 v[208:209], v[208:209], s[54:55] op_sel_hi:[1,0]
	v_pk_mul_f32 v[210:211], v[210:211], s[54:55] op_sel_hi:[1,0]
	s_waitcnt lgkmcnt(2)
	v_pk_fma_f32 v[240:241], v[240:241], v[160:161], v[208:209]
	v_pk_fma_f32 v[242:243], v[242:243], v[162:163], v[210:211]
	global_store_dwordx4 v[98:99], v[240:243], off sc1
	v_lshl_add_u64 v[98:99], v[98:99], 0, s[16:17]
	s_waitcnt vmcnt(8)
	v_pk_add_f32 v[212:213], v[212:213], v[184:185] op_sel_hi:[1,0] neg_lo:[0,1] neg_hi:[0,1]
	v_pk_add_f32 v[214:215], v[214:215], v[184:185] op_sel_hi:[1,0] neg_lo:[0,1] neg_hi:[0,1]
	v_pk_mul_f32 v[212:213], v[212:213], v[184:185] op_sel:[0,1]
	v_pk_mul_f32 v[214:215], v[214:215], v[184:185] op_sel:[0,1]
	v_pk_fma_f32 v[212:213], v[212:213], v[164:165], v[168:169]
	v_pk_fma_f32 v[214:215], v[214:215], v[166:167], v[170:171]
	v_pk_mul_f32 v[212:213], v[212:213], s[54:55] op_sel_hi:[1,0]
	v_pk_mul_f32 v[214:215], v[214:215], s[54:55] op_sel_hi:[1,0]
	s_waitcnt lgkmcnt(1)
	v_pk_fma_f32 v[244:245], v[244:245], v[160:161], v[212:213]
	v_pk_fma_f32 v[246:247], v[246:247], v[162:163], v[214:215]
	global_store_dwordx4 v[98:99], v[244:247], off sc1
	v_lshl_add_u64 v[98:99], v[98:99], 0, s[16:17]
	s_waitcnt vmcnt(7)
	v_pk_add_f32 v[216:217], v[216:217], v[186:187] op_sel_hi:[1,0] neg_lo:[0,1] neg_hi:[0,1]
	v_pk_add_f32 v[218:219], v[218:219], v[186:187] op_sel_hi:[1,0] neg_lo:[0,1] neg_hi:[0,1]
	v_pk_mul_f32 v[216:217], v[216:217], v[186:187] op_sel:[0,1]
	v_pk_mul_f32 v[218:219], v[218:219], v[186:187] op_sel:[0,1]
	v_pk_fma_f32 v[216:217], v[216:217], v[164:165], v[168:169]
	v_pk_fma_f32 v[218:219], v[218:219], v[166:167], v[170:171]
	v_pk_mul_f32 v[216:217], v[216:217], s[54:55] op_sel_hi:[1,0]
	v_pk_mul_f32 v[218:219], v[218:219], s[54:55] op_sel_hi:[1,0]
	s_waitcnt lgkmcnt(0)
	v_pk_fma_f32 v[248:249], v[248:249], v[160:161], v[216:217]
	v_pk_fma_f32 v[250:251], v[250:251], v[162:163], v[218:219]
	global_store_dwordx4 v[98:99], v[248:251], off sc1
	s_branch .LBB0_272
.Lm2epi_plain:
	s_waitcnt vmcnt(14)
	v_pk_mul_f32 v[188:189], v[188:189], s[54:55] op_sel_hi:[1,0]
	v_pk_mul_f32 v[190:191], v[190:191], s[54:55] op_sel_hi:[1,0]
	s_waitcnt lgkmcnt(7)
	v_pk_fma_f32 v[220:221], v[220:221], v[160:161], v[188:189]
	v_pk_fma_f32 v[222:223], v[222:223], v[162:163], v[190:191]
	global_store_dwordx4 v[98:99], v[220:223], off sc1
	v_lshl_add_u64 v[98:99], v[98:99], 0, s[16:17]
	s_waitcnt vmcnt(13)
	v_pk_mul_f32 v[192:193], v[192:193], s[54:55] op_sel_hi:[1,0]
	v_pk_mul_f32 v[194:195], v[194:195], s[54:55] op_sel_hi:[1,0]
	s_waitcnt lgkmcnt(6)
	v_pk_fma_f32 v[224:225], v[224:225], v[160:161], v[192:193]
	v_pk_fma_f32 v[226:227], v[226:227], v[162:163], v[194:195]
	global_store_dwordx4 v[98:99], v[224:227], off sc1
	v_lshl_add_u64 v[98:99], v[98:99], 0, s[16:17]
	s_waitcnt vmcnt(12)
	v_pk_mul_f32 v[196:197], v[196:197], s[54:55] op_sel_hi:[1,0]
	v_pk_mul_f32 v[198:199], v[198:199], s[54:55] op_sel_hi:[1,0]
	s_waitcnt lgkmcnt(5)
	v_pk_fma_f32 v[228:229], v[228:229], v[160:161], v[196:197]
	v_pk_fma_f32 v[230:231], v[230:231], v[162:163], v[198:199]
	global_store_dwordx4 v[98:99], v[228:231], off sc1
	v_lshl_add_u64 v[98:99], v[98:99], 0, s[16:17]
	s_waitcnt vmcnt(11)
	v_pk_mul_f32 v[200:201], v[200:201], s[54:55] op_sel_hi:[1,0]
	v_pk_mul_f32 v[202:203], v[202:203], s[54:55] op_sel_hi:[1,0]
	s_waitcnt lgkmcnt(4)
	v_pk_fma_f32 v[232:233], v[232:233], v[160:161], v[200:201]
	v_pk_fma_f32 v[234:235], v[234:235], v[162:163], v[202:203]
	global_store_dwordx4 v[98:99], v[232:235], off sc1
	v_lshl_add_u64 v[98:99], v[98:99], 0, s[16:17]
	s_waitcnt vmcnt(10)
	v_pk_mul_f32 v[204:205], v[204:205], s[54:55] op_sel_hi:[1,0]
	v_pk_mul_f32 v[206:207], v[206:207], s[54:55] op_sel_hi:[1,0]
	s_waitcnt lgkmcnt(3)
	v_pk_fma_f32 v[236:237], v[236:237], v[160:161], v[204:205]
	v_pk_fma_f32 v[238:239], v[238:239], v[162:163], v[206:207]
	global_store_dwordx4 v[98:99], v[236:239], off sc1
	v_lshl_add_u64 v[98:99], v[98:99], 0, s[16:17]
	s_waitcnt vmcnt(9)
	v_pk_mul_f32 v[208:209], v[208:209], s[54:55] op_sel_hi:[1,0]
	v_pk_mul_f32 v[210:211], v[210:211], s[54:55] op_sel_hi:[1,0]
	s_waitcnt lgkmcnt(2)
	v_pk_fma_f32 v[240:241], v[240:241], v[160:161], v[208:209]
	v_pk_fma_f32 v[242:243], v[242:243], v[162:163], v[210:211]
	global_store_dwordx4 v[98:99], v[240:243], off sc1
	v_lshl_add_u64 v[98:99], v[98:99], 0, s[16:17]
	s_waitcnt vmcnt(8)
	v_pk_mul_f32 v[212:213], v[212:213], s[54:55] op_sel_hi:[1,0]
	v_pk_mul_f32 v[214:215], v[214:215], s[54:55] op_sel_hi:[1,0]
	s_waitcnt lgkmcnt(1)
	v_pk_fma_f32 v[244:245], v[244:245], v[160:161], v[212:213]
	v_pk_fma_f32 v[246:247], v[246:247], v[162:163], v[214:215]
	global_store_dwordx4 v[98:99], v[244:247], off sc1
	v_lshl_add_u64 v[98:99], v[98:99], 0, s[16:17]
	s_waitcnt vmcnt(7)
	v_pk_mul_f32 v[216:217], v[216:217], s[54:55] op_sel_hi:[1,0]
	v_pk_mul_f32 v[218:219], v[218:219], s[54:55] op_sel_hi:[1,0]
	s_waitcnt lgkmcnt(0)
	v_pk_fma_f32 v[248:249], v[248:249], v[160:161], v[216:217]
	v_pk_fma_f32 v[250:251], v[250:251], v[162:163], v[218:219]
	global_store_dwordx4 v[98:99], v[248:251], off sc1
	s_branch .LBB0_272
